# final3 with all waves on rotated key-step loop, K fragment LDS reads issued right after the barrier ahead of the deferred exp/PV half; next-tile bias temporaries in spare VGPRs
# speedup vs baseline: 1.0037x; 1.0037x over previous
; #define LAS __attribute__((address_space(3)))
; __device__ __forceinline__ int crow(int r, int hi) { return (r & 3) + 8 * (r >> 2) + 4 * hi; }
; template <int MODE>
; __device__ __forceinline__ void step64(St& S, const bf16x8 (&qf)[4], int t, int qpos0, bool diag, bool first, float cq, float cfar, const LAS float* tab,
;                                        const LAS unsigned char* buf, unsigned vaddr, int r32, int hi) {
;     ...
;     for (int d0 = 0; d0 < 4; ++d0) { const int o = r32 * 128 + (((d0 * 2 + hi) ^ ((r32 >> 1) & 7)) << 4); ka[d0] = *(const LAS bf16x8*)(buf + o); kc[d0] = *(const LAS bf16x8*)(buf + 4096 + o); }
;     f32x16 sa, sb;
;     if (MODE == 1) {
;         const float nm = cq - S.m;
; #pragma unroll
;         for (int g = 0; g < 4; ++g) { const f32x4 c0 = *(const LAS f32x4*)(tab + t * 64 + 8 * g + 4 * hi), c1 = *(const LAS f32x4*)(tab + t * 64 + 32 + 8 * g + 4 * hi);
; #pragma unroll
;             for (int e = 0; e < 4; ++e) { sa[4 * g + e] = nm - c0[e]; sb[4 * g + e] = nm - c1[e]; } }
;     } else {
;         if (qpos0 - (t * 64 + 31) >= 128) {
;             const float c = cfar - S.m;
; #pragma unroll
;             for (int r = 0; r < 16; ++r) sa[r] = c;
;         } else {
;             const int dd = qpos0 + r32 - t * 64 + 128;
; #pragma unroll
;             for (int r = 0; r < 16; ++r) { int idx = dd - crow(r, hi); idx = idx < 0 ? 0 : (idx > 256 ? 256 : idx); sa[r] = tab[idx] - S.m; }
; template <int MODE> ...
;     ...
;     for (int s = T0; s < T1; ++s) {
;         const int t = SU_T(s);
;         const bool more = (s + 2 < T1);
;         if (more) { glds16(kg + (size_t)SU_T(s + 2) * 4096, kdst + s2); glds16(vg + (size_t)SU_T(s + 2) * 4096, vdst + s2); }
;         LAS unsigned char* buf = ring + s0;
;         if (t >= t_lo && t < t_hi)
;             step64<MODE>(S, qf, t, qpos0, t == t_hi - 1, REV ? (t == t_hi - 1) : (t == t_lo), cq, cfar, tab, buf, (unsigned)(unsigned long)(buf + 8192) + vl, r32, hi);
.LBB0_605:
	s_mov_b32 s50, s0
	s_sub_i32 s34, s41, 8
	s_max_i32 s34, s34, 0
	s_cmp_gt_i32 s44, s41
	s_cbranch_scc1 .Lk0_noK
	s_cmp_lt_i32 s44, s34
	s_cbranch_scc1 .Lk0_noK
	s_add_i32 s2, s50, 0
	v_add_u32_e32 v0, s2, v152
	v_add_u32_e32 v14, s2, v153
	v_add_u32_e32 v15, s2, v154
	v_add_u32_e32 v234, s2, v155
	ds_read_b128 v[186:189], v0 offset:18432
	ds_read_b128 v[194:197], v14 offset:18432
	ds_read_b128 v[202:205], v15 offset:18432
	ds_read_b128 v[210:213], v234 offset:18432
	ds_read_b128 v[190:193], v0 offset:22528
	ds_read_b128 v[198:201], v14 offset:22528
	ds_read_b128 v[206:209], v15 offset:22528
	ds_read_b128 v[214:217], v234 offset:22528
.Lk0_noK:
	s_add_i32 s0, s44, 2
	s_cmp_ge_u32 s0, s15
	s_cselect_b64 s[46:47], -1, 0
	s_and_b64 vcc, exec, s[46:47]
	s_cbranch_vccnz .Lk0_nodma
	s_add_i32 s1, s49, s24
	s_mov_b32 s2, m0
	s_mov_b32 m0, s1
	s_nop 0
	global_load_lds_dwordx4 v[124:125], off
	s_add_i32 s0, s49, s25
	s_mov_b32 m0, s0
	s_nop 0
	global_load_lds_dwordx4 v[122:123], off
	s_mov_b32 m0, s2
.Lk0_nodma:
	s_cmp_le_i32 s44, s34
	s_cbranch_scc1 .Lk0_noY
	s_add_i32 s35, s41, 1
	s_cmp_gt_i32 s44, s35
	s_cbranch_scc1 .Lk0_noY
	v_exp_f32_e32 v48, v48
	v_exp_f32_e32 v49, v49
	v_exp_f32_e32 v50, v50
	v_exp_f32_e32 v51, v51
	v_exp_f32_e32 v52, v52
	v_exp_f32_e32 v53, v53
	v_exp_f32_e32 v54, v54
	v_exp_f32_e32 v55, v55
	v_cvt_pk_bf16_f32 v218, v48, v49
	v_cvt_pk_bf16_f32 v219, v50, v51
	v_cvt_pk_bf16_f32 v220, v52, v53
	v_cvt_pk_bf16_f32 v221, v54, v55
	v_exp_f32_e32 v56, v56
	v_exp_f32_e32 v57, v57
	v_mfma_f32_32x32x16_bf16 v[32:47], v[112:115], v[218:221], v[32:47]
	s_cmp_gt_i32 s44, s41
	s_cbranch_scc1 .Lk0a_notab
	s_add_i32 s35, s48, 63
	s_min_i32 s35, s35, 192
	s_lshl_b32 s35, s35, 2
	v_subrev_u32_e32 v235, s35, v238
	s_waitcnt lgkmcnt(0)
	ds_read_b128 v[158:161], v235
	ds_read_b128 v[162:165], v235 offset:32
	ds_read_b128 v[166:169], v235 offset:64
	ds_read_b128 v[170:173], v235 offset:96
	ds_read_b128 v[174:177], v235 offset:128
	ds_read_b128 v[180:183], v235 offset:160
	ds_read_b128 v[116:119], v235 offset:192
	ds_read_b64 v[236:237], v235 offset:224
	ds_read_b32 v178, v235 offset:232
	ds_read_b32 v185, v235 offset:236
; template <int MODE>
; __device__ __forceinline__ void step64(St& S, const bf16x8 (&qf)[4], int t, int qpos0, bool diag, bool first, float cq, float cfar, const LAS float* tab,
;                                        const LAS unsigned char* buf, unsigned vaddr, int r32, int hi) {
;     ...
;         if (qpos0 - (t * 64 + 31) >= 128) {
;             const float c = cfar - S.m;
; #pragma unroll
;             for (int r = 0; r < 16; ++r) sa[r] = c;
;         } else {
;             const int dd = qpos0 + r32 - t * 64 + 128;
; #pragma unroll
;             for (int r = 0; r < 16; ++r) { int idx = dd - crow(r, hi); idx = idx < 0 ? 0 : (idx > 256 ? 256 : idx); sa[r] = tab[idx] - S.m; }
;     ...
;     for (int r = 0; r < 16; ++r) { sa[r] = __builtin_amdgcn_exp2f(sa[r]); sb[r] = __builtin_amdgcn_exp2f(sb[r]); }
;     asm volatile("s_waitcnt lgkmcnt(0)" ::: "memory");
;     __builtin_amdgcn_sched_barrier(0);
;     u32x4 pa0, pa1, pb0, pb1;
;     pa0.x = pk2(sa[0], sa[1]); pa0.y = pk2(sa[2], sa[3]); pa0.z = pk2(sa[4], sa[5]); pa0.w = pk2(sa[6], sa[7]);
;     pa1.x = pk2(sa[8], sa[9]); pa1.y = pk2(sa[10], sa[11]); pa1.z = pk2(sa[12], sa[13]); pa1.w = pk2(sa[14], sa[15]);
;     pb0.x = pk2(sb[0], sb[1]); pb0.y = pk2(sb[2], sb[3]); pb0.z = pk2(sb[4], sb[5]); pb0.w = pk2(sb[6], sb[7]);
;     pb1.x = pk2(sb[8], sb[9]); pb1.y = pk2(sb[10], sb[11]); pb1.z = pk2(sb[12], sb[13]); pb1.w = pk2(sb[14], sb[15]);
;     ...
;     S.o0 = __builtin_amdgcn_mfma_f32_32x32x16_bf16(ATT_VF(0), ATT_PF(pa0), S.o0, 0, 0, 0);
;     S.o1 = __builtin_amdgcn_mfma_f32_32x32x16_bf16(ATT_VF(2), ATT_PF(pa0), S.o1, 0, 0, 0);
;     S.o0 = __builtin_amdgcn_mfma_f32_32x32x16_bf16(ATT_VF(1), ATT_PF(pa1), S.o0, 0, 0, 0);
;     S.o1 = __builtin_amdgcn_mfma_f32_32x32x16_bf16(ATT_VF(3), ATT_PF(pa1), S.o1, 0, 0, 0);
;     S.o0 = __builtin_amdgcn_mfma_f32_32x32x16_bf16(ATT_VF(4), ATT_PF(pb0), S.o0, 0, 0, 0);
;     S.o1 = __builtin_amdgcn_mfma_f32_32x32x16_bf16(ATT_VF(6), ATT_PF(pb0), S.o1, 0, 0, 0);
;     S.o0 = __builtin_amdgcn_mfma_f32_32x32x16_bf16(ATT_VF(5), ATT_PF(pb1), S.o0, 0, 0, 0);
;     S.o1 = __builtin_amdgcn_mfma_f32_32x32x16_bf16(ATT_VF(7), ATT_PF(pb1), S.o1, 0, 0, 0);
;     ...
;     float l0 = 0.f, l1 = 0.f, l2 = 0.f, l3 = 0.f;
; #pragma unroll
;     for (int r = 0; r < 16; r += 2) { l0 += sa[r]; l1 += sa[r + 1]; l2 += sb[r]; l3 += sb[r + 1]; }
;     S.l += (l0 + l1) + (l2 + l3);
.Lk0a_notab:
	v_exp_f32_e32 v58, v58
	v_exp_f32_e32 v59, v59
	v_exp_f32_e32 v60, v60
	v_exp_f32_e32 v61, v61
	v_exp_f32_e32 v62, v62
	v_exp_f32_e32 v63, v63
	v_mfma_f32_32x32x16_bf16 v[16:31], v[108:111], v[218:221], v[16:31]
	v_cvt_pk_bf16_f32 v222, v56, v57
	v_cvt_pk_bf16_f32 v223, v58, v59
	v_cvt_pk_bf16_f32 v224, v60, v61
	v_cvt_pk_bf16_f32 v225, v62, v63
	v_add_f32_e32 v0, v48, v50
	v_add_f32_e32 v0, v0, v52
	v_add_f32_e32 v14, v49, v51
	v_add_f32_e32 v14, v14, v53
	v_mfma_f32_32x32x16_bf16 v[32:47], v[104:107], v[222:225], v[32:47]
	v_exp_f32_e32 v64, v64
	v_exp_f32_e32 v65, v65
	v_exp_f32_e32 v66, v66
	v_exp_f32_e32 v67, v67
	v_exp_f32_e32 v68, v68
	v_exp_f32_e32 v69, v69
	v_exp_f32_e32 v70, v70
	v_exp_f32_e32 v71, v71
	v_mfma_f32_32x32x16_bf16 v[16:31], v[100:103], v[222:225], v[16:31]
	v_cvt_pk_bf16_f32 v226, v64, v65
	v_cvt_pk_bf16_f32 v227, v66, v67
	v_cvt_pk_bf16_f32 v228, v68, v69
	v_cvt_pk_bf16_f32 v229, v70, v71
	v_add_f32_e32 v0, v0, v54
	v_add_f32_e32 v0, v0, v56
	v_add_f32_e32 v14, v14, v55
	v_add_f32_e32 v14, v14, v57
	v_mfma_f32_32x32x16_bf16 v[32:47], v[96:99], v[226:229], v[32:47]
	v_exp_f32_e32 v72, v72
	v_exp_f32_e32 v73, v73
	v_exp_f32_e32 v74, v74
	v_exp_f32_e32 v75, v75
	v_exp_f32_e32 v76, v76
	v_exp_f32_e32 v77, v77
	v_exp_f32_e32 v78, v78
	v_exp_f32_e32 v79, v79
	v_mfma_f32_32x32x16_bf16 v[16:31], v[10:13], v[226:229], v[16:31]
	v_cvt_pk_bf16_f32 v230, v72, v73
	v_cvt_pk_bf16_f32 v231, v74, v75
	v_cvt_pk_bf16_f32 v232, v76, v77
	v_cvt_pk_bf16_f32 v233, v78, v79
	v_add_f32_e32 v0, v0, v58
	v_add_f32_e32 v0, v0, v60
	v_add_f32_e32 v0, v0, v62
	v_add_f32_e32 v14, v14, v59
	v_add_f32_e32 v14, v14, v61
	v_add_f32_e32 v14, v14, v63
	v_mfma_f32_32x32x16_bf16 v[32:47], v[6:9], v[230:233], v[32:47]
	v_add_f32_e32 v15, v64, v66
	v_add_f32_e32 v15, v15, v68
	v_add_f32_e32 v15, v15, v70
	v_add_f32_e32 v15, v15, v72
	v_add_f32_e32 v234, v65, v67
	v_add_f32_e32 v234, v234, v69
	v_add_f32_e32 v234, v234, v71
	v_add_f32_e32 v234, v234, v73
	v_mfma_f32_32x32x16_bf16 v[16:31], v[2:5], v[230:233], v[16:31]
	v_add_f32_e32 v15, v15, v74
	v_add_f32_e32 v15, v15, v76
	v_add_f32_e32 v15, v15, v78
	v_add_f32_e32 v234, v234, v75
	v_add_f32_e32 v234, v234, v77
	v_add_f32_e32 v234, v234, v79
	v_add_f32_e32 v0, v0, v14
	v_add_f32_e32 v15, v15, v234
	v_add_f32_e32 v0, v0, v15
	v_add_f32_e32 v150, v150, v0
	s_cmp_gt_i32 s44, s41
	s_cbranch_scc1 .Lk0a_end
	s_waitcnt lgkmcnt(0)
	v_sub_f32_e32 v48, v158, v157
	v_sub_f32_e32 v49, v159, v157
	v_sub_f32_e32 v50, v160, v157
	v_sub_f32_e32 v51, v161, v157
	v_sub_f32_e32 v52, v162, v157
	v_sub_f32_e32 v53, v163, v157
	v_sub_f32_e32 v54, v164, v157
	v_sub_f32_e32 v55, v165, v157
	v_sub_f32_e32 v56, v166, v157
	v_sub_f32_e32 v57, v167, v157
	v_sub_f32_e32 v58, v168, v157
	v_sub_f32_e32 v59, v169, v157
	v_sub_f32_e32 v60, v170, v157
	v_sub_f32_e32 v61, v171, v157
	v_sub_f32_e32 v62, v172, v157
	v_sub_f32_e32 v63, v173, v157
	v_sub_f32_e32 v64, v174, v157
	v_sub_f32_e32 v65, v175, v157
	v_sub_f32_e32 v66, v176, v157
	v_sub_f32_e32 v67, v177, v157
	v_sub_f32_e32 v68, v180, v157
	v_sub_f32_e32 v69, v181, v157
	v_sub_f32_e32 v70, v182, v157
	v_sub_f32_e32 v71, v183, v157
	v_sub_f32_e32 v72, v116, v157
	v_sub_f32_e32 v73, v117, v157
	v_sub_f32_e32 v74, v118, v157
	v_sub_f32_e32 v75, v119, v157
	v_sub_f32_e32 v76, v236, v157
	v_sub_f32_e32 v77, v237, v157
	v_sub_f32_e32 v78, v178, v157
	v_sub_f32_e32 v79, v185, v157
.Lk0a_end:
.Lk0_noY:
	s_cmp_gt_i32 s44, s41
	s_cbranch_scc1 .Lk0_norescale
	s_sub_i32 s34, s41, 8
	s_max_i32 s34, s34, 0
	s_cmp_lt_i32 s44, s34
	s_cbranch_scc1 .Lk0_norescale
	s_add_i32 s2, s50, 0
	s_add_i32 s5, s2, 0x6800
	s_sub_i32 s34, s41, 8
	s_max_i32 s34, s34, 0
	v_add_u32_e32 v0, s5, v151
	s_cmp_eq_u32 s44, s34
	s_cbranch_scc0 .Lk0_have_init
	s_add_i32 s35, s48, 63
	s_min_i32 s35, s35, 192
	s_lshl_b32 s35, s35, 2
	v_subrev_u32_e32 v15, s35, v238
	ds_read_b128 v[112:115], v15
	ds_read_b128 v[104:107], v15 offset:32
	ds_read_b128 v[108:111], v15 offset:64
	ds_read_b128 v[100:103], v15 offset:96
	ds_read_b128 v[96:99], v15 offset:128
	ds_read_b128 v[6:9], v15 offset:160
	ds_read_b128 v[10:13], v15 offset:192
	ds_read_b128 v[2:5], v15 offset:224
	s_waitcnt lgkmcnt(0)
	v_sub_f32_e32 v48, v112, v157
	v_sub_f32_e32 v49, v113, v157
	v_sub_f32_e32 v50, v114, v157
	v_sub_f32_e32 v51, v115, v157
	v_sub_f32_e32 v52, v104, v157
	v_sub_f32_e32 v53, v105, v157
	v_sub_f32_e32 v54, v106, v157
	v_sub_f32_e32 v55, v107, v157
	v_sub_f32_e32 v56, v108, v157
	v_sub_f32_e32 v57, v109, v157
	v_sub_f32_e32 v58, v110, v157
	v_sub_f32_e32 v59, v111, v157
	v_sub_f32_e32 v60, v100, v157
	v_sub_f32_e32 v61, v101, v157
	v_sub_f32_e32 v62, v102, v157
	v_sub_f32_e32 v63, v103, v157
	v_sub_f32_e32 v64, v96, v157
	v_sub_f32_e32 v65, v97, v157
	v_sub_f32_e32 v66, v98, v157
	v_sub_f32_e32 v67, v99, v157
	v_sub_f32_e32 v68, v6, v157
	v_sub_f32_e32 v69, v7, v157
	v_sub_f32_e32 v70, v8, v157
	v_sub_f32_e32 v71, v9, v157
	v_sub_f32_e32 v72, v10, v157
	v_sub_f32_e32 v73, v11, v157
	v_sub_f32_e32 v74, v12, v157
	v_sub_f32_e32 v75, v13, v157
	v_sub_f32_e32 v76, v2, v157
	v_sub_f32_e32 v77, v3, v157
	v_sub_f32_e32 v78, v4, v157
	v_sub_f32_e32 v79, v5, v157
	s_nop 1

; __device__ __forceinline__ unsigned pk2(float lo, float hi) { f32x2_t v = {lo, hi}; bf16x2_t b = __builtin_convertvector(v, bf16x2_t); return __builtin_bit_cast(unsigned, b); }
; template <int MODE>
; __device__ __forceinline__ void step64(St& S, const bf16x8 (&qf)[4], int t, int qpos0, bool diag, bool first, float cq, float cfar, const LAS float* tab,
;                                        const LAS unsigned char* buf, unsigned vaddr, int r32, int hi) {
;     ...
;     for (int r = 0; r < 16; ++r) { sa[r] = __builtin_amdgcn_exp2f(sa[r]); sb[r] = __builtin_amdgcn_exp2f(sb[r]); }
;     asm volatile("s_waitcnt lgkmcnt(0)" ::: "memory");
;     __builtin_amdgcn_sched_barrier(0);
;     u32x4 pa0, pa1, pb0, pb1;
;     pa0.x = pk2(sa[0], sa[1]); pa0.y = pk2(sa[2], sa[3]); pa0.z = pk2(sa[4], sa[5]); pa0.w = pk2(sa[6], sa[7]);
;     pa1.x = pk2(sa[8], sa[9]); pa1.y = pk2(sa[10], sa[11]); pa1.z = pk2(sa[12], sa[13]); pa1.w = pk2(sa[14], sa[15]);
;     pb0.x = pk2(sb[0], sb[1]); pb0.y = pk2(sb[2], sb[3]); pb0.z = pk2(sb[4], sb[5]); pb0.w = pk2(sb[6], sb[7]);
;     pb1.x = pk2(sb[8], sb[9]); pb1.y = pk2(sb[10], sb[11]); pb1.z = pk2(sb[12], sb[13]); pb1.w = pk2(sb[14], sb[15]);
;     ...
;     S.o0 = __builtin_amdgcn_mfma_f32_32x32x16_bf16(ATT_VF(0), ATT_PF(pa0), S.o0, 0, 0, 0);
;     S.o1 = __builtin_amdgcn_mfma_f32_32x32x16_bf16(ATT_VF(2), ATT_PF(pa0), S.o1, 0, 0, 0);
;     S.o0 = __builtin_amdgcn_mfma_f32_32x32x16_bf16(ATT_VF(1), ATT_PF(pa1), S.o0, 0, 0, 0);
;     S.o1 = __builtin_amdgcn_mfma_f32_32x32x16_bf16(ATT_VF(3), ATT_PF(pa1), S.o1, 0, 0, 0);
.Lk0_epi:
	s_add_i32 s35, s41, 1
	s_cmp_gt_i32 s44, s35
	s_cbranch_scc1 .Lk0_done
	v_exp_f32_e32 v48, v48
	v_exp_f32_e32 v49, v49
	v_exp_f32_e32 v50, v50
	v_exp_f32_e32 v51, v51
	v_exp_f32_e32 v52, v52
	v_exp_f32_e32 v53, v53
	v_exp_f32_e32 v54, v54
	v_exp_f32_e32 v55, v55
	v_cvt_pk_bf16_f32 v218, v48, v49
	v_cvt_pk_bf16_f32 v219, v50, v51
	v_cvt_pk_bf16_f32 v220, v52, v53
	v_cvt_pk_bf16_f32 v221, v54, v55
	v_exp_f32_e32 v56, v56
	v_exp_f32_e32 v57, v57
	v_mfma_f32_32x32x16_bf16 v[32:47], v[112:115], v[218:221], v[32:47]
	s_cmp_gt_i32 s44, s41
	s_cbranch_scc1 .Lk0b_notab
	s_add_i32 s35, s48, 63
	s_min_i32 s35, s35, 192
	s_lshl_b32 s35, s35, 2
	v_subrev_u32_e32 v235, s35, v238
	s_waitcnt lgkmcnt(0)
	ds_read_b128 v[158:161], v235
	ds_read_b128 v[162:165], v235 offset:32
	ds_read_b128 v[166:169], v235 offset:64
	ds_read_b128 v[170:173], v235 offset:96
	ds_read_b128 v[174:177], v235 offset:128
	ds_read_b128 v[180:183], v235 offset:160
	ds_read_b128 v[116:119], v235 offset:192
	ds_read_b64 v[236:237], v235 offset:224
	ds_read_b32 v178, v235 offset:232
	ds_read_b32 v185, v235 offset:236

; template <int MODE>
; __device__ __forceinline__ void step64(St& S, const bf16x8 (&qf)[4], int t, int qpos0, bool diag, bool first, float cq, float cfar, const LAS float* tab,
;                                        const LAS unsigned char* buf, unsigned vaddr, int r32, int hi) {
;     ...
;     for (int d0 = 0; d0 < 4; ++d0) { const int o = r32 * 128 + (((d0 * 2 + hi) ^ ((r32 >> 1) & 7)) << 4); ka[d0] = *(const LAS bf16x8*)(buf + o); kc[d0] = *(const LAS bf16x8*)(buf + 4096 + o); }
;     f32x16 sa, sb;
;     if (MODE == 1) {
;         const float nm = cq - S.m;
; #pragma unroll
;         for (int g = 0; g < 4; ++g) { const f32x4 c0 = *(const LAS f32x4*)(tab + t * 64 + 8 * g + 4 * hi), c1 = *(const LAS f32x4*)(tab + t * 64 + 32 + 8 * g + 4 * hi);
; #pragma unroll
;             for (int e = 0; e < 4; ++e) { sa[4 * g + e] = nm - c0[e]; sb[4 * g + e] = nm - c1[e]; } }
;     ...
;     for (int r = 0; r < 16; ++r) { sa[r] = __builtin_amdgcn_exp2f(sa[r]); sb[r] = __builtin_amdgcn_exp2f(sb[r]); }
;     asm volatile("s_waitcnt lgkmcnt(0)" ::: "memory");
;     __builtin_amdgcn_sched_barrier(0);
;     u32x4 pa0, pa1, pb0, pb1;
;     pa0.x = pk2(sa[0], sa[1]); pa0.y = pk2(sa[2], sa[3]); pa0.z = pk2(sa[4], sa[5]); pa0.w = pk2(sa[6], sa[7]);
;     pa1.x = pk2(sa[8], sa[9]); pa1.y = pk2(sa[10], sa[11]); pa1.z = pk2(sa[12], sa[13]); pa1.w = pk2(sa[14], sa[15]);
;     pb0.x = pk2(sb[0], sb[1]); pb0.y = pk2(sb[2], sb[3]); pb0.z = pk2(sb[4], sb[5]); pb0.w = pk2(sb[6], sb[7]);
;     pb1.x = pk2(sb[8], sb[9]); pb1.y = pk2(sb[10], sb[11]); pb1.z = pk2(sb[12], sb[13]); pb1.w = pk2(sb[14], sb[15]);
;     ...
;     S.o0 = __builtin_amdgcn_mfma_f32_32x32x16_bf16(ATT_VF(0), ATT_PF(pa0), S.o0, 0, 0, 0);
;     S.o1 = __builtin_amdgcn_mfma_f32_32x32x16_bf16(ATT_VF(2), ATT_PF(pa0), S.o1, 0, 0, 0);
;     S.o0 = __builtin_amdgcn_mfma_f32_32x32x16_bf16(ATT_VF(1), ATT_PF(pa1), S.o0, 0, 0, 0);
;     S.o1 = __builtin_amdgcn_mfma_f32_32x32x16_bf16(ATT_VF(3), ATT_PF(pa1), S.o1, 0, 0, 0);
;     S.o0 = __builtin_amdgcn_mfma_f32_32x32x16_bf16(ATT_VF(4), ATT_PF(pb0), S.o0, 0, 0, 0);
;     S.o1 = __builtin_amdgcn_mfma_f32_32x32x16_bf16(ATT_VF(6), ATT_PF(pb0), S.o1, 0, 0, 0);
;     S.o0 = __builtin_amdgcn_mfma_f32_32x32x16_bf16(ATT_VF(5), ATT_PF(pb1), S.o0, 0, 0, 0);
;     S.o1 = __builtin_amdgcn_mfma_f32_32x32x16_bf16(ATT_VF(7), ATT_PF(pb1), S.o1, 0, 0, 0);
;     ...
;     float l0 = 0.f, l1 = 0.f, l2 = 0.f, l3 = 0.f;
; #pragma unroll
.LBB0_636:
	s_cmp_ge_u32 s19, s33
	s_cselect_b64 s[24:25], -1, 0
	s_mov_b32 s11, s0
	s_add_i32 s22, s1, -1
	s_cmp_gt_i32 s22, s28
	s_cbranch_scc1 .Lk1_noK
	s_add_i32 s6, s11, 0
	v_add_u32_e32 v0, s6, v143
	v_add_u32_e32 v14, s6, v144
	v_add_u32_e32 v15, s6, v145
	v_add_u32_e32 v151, s6, v146
	ds_read_b128 v[186:189], v0 offset:18432
	ds_read_b128 v[194:197], v14 offset:18432
	ds_read_b128 v[202:205], v15 offset:18432
	ds_read_b128 v[210:213], v151 offset:18432
	ds_read_b128 v[190:193], v0 offset:22528
	ds_read_b128 v[198:201], v14 offset:22528
	ds_read_b128 v[206:209], v15 offset:22528
	ds_read_b128 v[214:217], v151 offset:22528
.Lk1_noK:
	s_and_b64 vcc, exec, s[24:25]
	s_cbranch_vccnz .Lk1_nodma
	s_add_i32 s4, s12, s20
	s_mov_b32 s5, m0
	s_mov_b32 m0, s4
	s_nop 0
	global_load_lds_dwordx4 v[118:119], off
	s_add_i32 s0, s12, s3
	s_mov_b32 m0, s0
	s_nop 0
	global_load_lds_dwordx4 v[116:117], off
	s_mov_b32 m0, s5
.Lk1_nodma:
	s_cmp_lt_i32 s22, s28
	s_cbranch_scc0 .Lk1_noY
	v_exp_f32_e32 v48, v48
	v_exp_f32_e32 v49, v49
	v_exp_f32_e32 v50, v50
	v_exp_f32_e32 v51, v51
	v_exp_f32_e32 v52, v52
	v_exp_f32_e32 v53, v53
	v_exp_f32_e32 v54, v54
	v_exp_f32_e32 v55, v55
	v_cvt_pk_bf16_f32 v152, v48, v49
	v_cvt_pk_bf16_f32 v153, v50, v51
	v_cvt_pk_bf16_f32 v154, v52, v53
	v_cvt_pk_bf16_f32 v155, v54, v55
	v_exp_f32_e32 v56, v56
	v_exp_f32_e32 v57, v57
	v_mfma_f32_32x32x16_bf16 v[32:47], v[112:115], v[152:155], v[32:47]
	s_waitcnt lgkmcnt(0)
	ds_read_b128 v[164:167], v148
	ds_read_b128 v[168:171], v148 offset:32
	ds_read_b128 v[172:175], v148 offset:64
	ds_read_b128 v[180:183], v148 offset:96
	ds_read_b128 v[218:221], v148 offset:128
	ds_read_b128 v[222:225], v148 offset:160
	ds_read_b128 v[226:229], v148 offset:192
	ds_read_b128 v[230:233], v148 offset:224
	v_exp_f32_e32 v58, v58
	v_exp_f32_e32 v59, v59
	v_exp_f32_e32 v60, v60
	v_exp_f32_e32 v61, v61
	v_exp_f32_e32 v62, v62
	v_exp_f32_e32 v63, v63
	v_mfma_f32_32x32x16_bf16 v[16:31], v[108:111], v[152:155], v[16:31]
	v_cvt_pk_bf16_f32 v156, v56, v57
	v_cvt_pk_bf16_f32 v157, v58, v59
	v_cvt_pk_bf16_f32 v158, v60, v61
	v_cvt_pk_bf16_f32 v159, v62, v63
	v_add_f32_e32 v0, v48, v50
	v_add_f32_e32 v0, v0, v52
	v_add_f32_e32 v14, v49, v51
	v_add_f32_e32 v14, v14, v53
	v_mfma_f32_32x32x16_bf16 v[32:47], v[104:107], v[156:159], v[32:47]
	v_exp_f32_e32 v64, v64
	v_exp_f32_e32 v65, v65
	v_exp_f32_e32 v66, v66
	v_exp_f32_e32 v67, v67
	v_exp_f32_e32 v68, v68
	v_exp_f32_e32 v69, v69
	v_exp_f32_e32 v70, v70
	v_exp_f32_e32 v71, v71
	v_mfma_f32_32x32x16_bf16 v[16:31], v[100:103], v[156:159], v[16:31]
	v_cvt_pk_bf16_f32 v160, v64, v65
	v_cvt_pk_bf16_f32 v161, v66, v67
	v_cvt_pk_bf16_f32 v162, v68, v69
	v_cvt_pk_bf16_f32 v163, v70, v71
	v_add_f32_e32 v0, v0, v54
	v_add_f32_e32 v0, v0, v56
	v_add_f32_e32 v14, v14, v55
	v_add_f32_e32 v14, v14, v57
	v_mfma_f32_32x32x16_bf16 v[32:47], v[96:99], v[160:163], v[32:47]
	v_exp_f32_e32 v72, v72
	v_exp_f32_e32 v73, v73
	v_exp_f32_e32 v74, v74
	v_exp_f32_e32 v75, v75
	v_exp_f32_e32 v76, v76
	v_exp_f32_e32 v77, v77
	v_exp_f32_e32 v78, v78
	v_exp_f32_e32 v79, v79
	v_mfma_f32_32x32x16_bf16 v[16:31], v[10:13], v[160:163], v[16:31]
	v_cvt_pk_bf16_f32 v234, v72, v73
	v_cvt_pk_bf16_f32 v235, v74, v75
	v_cvt_pk_bf16_f32 v236, v76, v77
	v_cvt_pk_bf16_f32 v237, v78, v79
	v_add_f32_e32 v0, v0, v58
	v_add_f32_e32 v0, v0, v60
	v_add_f32_e32 v0, v0, v62
	v_add_f32_e32 v14, v14, v59
	v_add_f32_e32 v14, v14, v61
	v_add_f32_e32 v14, v14, v63
	v_mfma_f32_32x32x16_bf16 v[32:47], v[6:9], v[234:237], v[32:47]
	v_add_f32_e32 v15, v64, v66
	v_add_f32_e32 v15, v15, v68
	v_add_f32_e32 v15, v15, v70
	v_add_f32_e32 v15, v15, v72
	v_add_f32_e32 v151, v65, v67
	v_add_f32_e32 v151, v151, v69
	v_add_f32_e32 v151, v151, v71
	v_add_f32_e32 v151, v151, v73
	v_mfma_f32_32x32x16_bf16 v[16:31], v[2:5], v[234:237], v[16:31]
	v_add_f32_e32 v15, v15, v74
	v_add_f32_e32 v15, v15, v76
	v_add_f32_e32 v15, v15, v78
	v_add_f32_e32 v151, v151, v75
	v_add_f32_e32 v151, v151, v77
	v_add_f32_e32 v151, v151, v79
	v_add_f32_e32 v0, v0, v14
	v_add_f32_e32 v15, v15, v151
	v_add_f32_e32 v0, v0, v15
	v_add_f32_e32 v149, v149, v0
	v_sub_f32_e32 v151, v142, v150
	s_waitcnt lgkmcnt(0)
	v_sub_f32_e32 v48, v151, v164
	v_sub_f32_e32 v49, v151, v165
	v_sub_f32_e32 v50, v151, v166
	v_sub_f32_e32 v51, v151, v167
	v_sub_f32_e32 v52, v151, v168
	v_sub_f32_e32 v53, v151, v169
	v_sub_f32_e32 v54, v151, v170
	v_sub_f32_e32 v55, v151, v171
	v_sub_f32_e32 v56, v151, v172
	v_sub_f32_e32 v57, v151, v173
	v_sub_f32_e32 v58, v151, v174
	v_sub_f32_e32 v59, v151, v175
	v_sub_f32_e32 v60, v151, v180
	v_sub_f32_e32 v61, v151, v181
	v_sub_f32_e32 v62, v151, v182
	v_sub_f32_e32 v63, v151, v183
	v_sub_f32_e32 v64, v151, v218
	v_sub_f32_e32 v65, v151, v219
	v_sub_f32_e32 v66, v151, v220
	v_sub_f32_e32 v67, v151, v221
	v_sub_f32_e32 v68, v151, v222
	v_sub_f32_e32 v69, v151, v223
	v_sub_f32_e32 v70, v151, v224
	v_sub_f32_e32 v71, v151, v225
	v_sub_f32_e32 v72, v151, v226
	v_sub_f32_e32 v73, v151, v227
	v_sub_f32_e32 v74, v151, v228
	v_sub_f32_e32 v75, v151, v229
	v_sub_f32_e32 v76, v151, v230
	v_sub_f32_e32 v77, v151, v231
	v_sub_f32_e32 v78, v151, v232
	v_sub_f32_e32 v79, v151, v233
.Lk1_noY:
	s_cmp_gt_i32 s22, s28
	s_cbranch_scc1 .Lk1_norescale
	s_add_i32 s6, s11, 0
	s_add_i32 s5, s6, 0x6800
	s_add_i32 s4, s15, s1
	s_cmp_eq_u32 s4, 1
	v_add_u32_e32 v0, s5, v147
	s_cbranch_scc0 .Lk1_have_init
	ds_read_b128 v[112:115], v148
	ds_read_b128 v[104:107], v148 offset:32
	ds_read_b128 v[108:111], v148 offset:64
	ds_read_b128 v[100:103], v148 offset:96
	ds_read_b128 v[96:99], v148 offset:128
	ds_read_b128 v[6:9], v148 offset:160
	ds_read_b128 v[10:13], v148 offset:192
	ds_read_b128 v[2:5], v148 offset:224
	v_sub_f32_e32 v151, v142, v150
	s_waitcnt lgkmcnt(0)
	v_sub_f32_e32 v48, v151, v112
	v_sub_f32_e32 v49, v151, v113
	v_sub_f32_e32 v50, v151, v114
	v_sub_f32_e32 v51, v151, v115
	v_sub_f32_e32 v52, v151, v104
	v_sub_f32_e32 v53, v151, v105
	v_sub_f32_e32 v54, v151, v106
	v_sub_f32_e32 v55, v151, v107
	v_sub_f32_e32 v56, v151, v108
	v_sub_f32_e32 v57, v151, v109
	v_sub_f32_e32 v58, v151, v110
	v_sub_f32_e32 v59, v151, v111
	v_sub_f32_e32 v60, v151, v100
	v_sub_f32_e32 v61, v151, v101
	v_sub_f32_e32 v62, v151, v102
	v_sub_f32_e32 v63, v151, v103
	v_sub_f32_e32 v64, v151, v96
	v_sub_f32_e32 v65, v151, v97
	v_sub_f32_e32 v66, v151, v98
	v_sub_f32_e32 v67, v151, v99
	v_sub_f32_e32 v68, v151, v6
	v_sub_f32_e32 v69, v151, v7
	v_sub_f32_e32 v70, v151, v8
	v_sub_f32_e32 v71, v151, v9
	v_sub_f32_e32 v72, v151, v10
	v_sub_f32_e32 v73, v151, v11
	v_sub_f32_e32 v74, v151, v12
	v_sub_f32_e32 v75, v151, v13
	v_sub_f32_e32 v76, v151, v2
	v_sub_f32_e32 v77, v151, v3
	v_sub_f32_e32 v78, v151, v4
	v_sub_f32_e32 v79, v151, v5
	s_nop 1

; __device__ __forceinline__ unsigned pk2(float lo, float hi) { f32x2_t v = {lo, hi}; bf16x2_t b = __builtin_convertvector(v, bf16x2_t); return __builtin_bit_cast(unsigned, b); }
; template <int MODE>
; __device__ __forceinline__ void step64(St& S, const bf16x8 (&qf)[4], int t, int qpos0, bool diag, bool first, float cq, float cfar, const LAS float* tab,
;                                        const LAS unsigned char* buf, unsigned vaddr, int r32, int hi) {
;     ...
;     for (int r = 0; r < 16; ++r) { sa[r] = __builtin_amdgcn_exp2f(sa[r]); sb[r] = __builtin_amdgcn_exp2f(sb[r]); }
;     asm volatile("s_waitcnt lgkmcnt(0)" ::: "memory");
;     __builtin_amdgcn_sched_barrier(0);
;     u32x4 pa0, pa1, pb0, pb1;
;     pa0.x = pk2(sa[0], sa[1]); pa0.y = pk2(sa[2], sa[3]); pa0.z = pk2(sa[4], sa[5]); pa0.w = pk2(sa[6], sa[7]);
;     pa1.x = pk2(sa[8], sa[9]); pa1.y = pk2(sa[10], sa[11]); pa1.z = pk2(sa[12], sa[13]); pa1.w = pk2(sa[14], sa[15]);
;     pb0.x = pk2(sb[0], sb[1]); pb0.y = pk2(sb[2], sb[3]); pb0.z = pk2(sb[4], sb[5]); pb0.w = pk2(sb[6], sb[7]);
;     pb1.x = pk2(sb[8], sb[9]); pb1.y = pk2(sb[10], sb[11]); pb1.z = pk2(sb[12], sb[13]); pb1.w = pk2(sb[14], sb[15]);
;     ...
;     S.o0 = __builtin_amdgcn_mfma_f32_32x32x16_bf16(ATT_VF(0), ATT_PF(pa0), S.o0, 0, 0, 0);
;     S.o1 = __builtin_amdgcn_mfma_f32_32x32x16_bf16(ATT_VF(2), ATT_PF(pa0), S.o1, 0, 0, 0);
;     S.o0 = __builtin_amdgcn_mfma_f32_32x32x16_bf16(ATT_VF(1), ATT_PF(pa1), S.o0, 0, 0, 0);
;     S.o1 = __builtin_amdgcn_mfma_f32_32x32x16_bf16(ATT_VF(3), ATT_PF(pa1), S.o1, 0, 0, 0);
;     S.o0 = __builtin_amdgcn_mfma_f32_32x32x16_bf16(ATT_VF(4), ATT_PF(pb0), S.o0, 0, 0, 0);
;     S.o1 = __builtin_amdgcn_mfma_f32_32x32x16_bf16(ATT_VF(6), ATT_PF(pb0), S.o1, 0, 0, 0);
;     S.o0 = __builtin_amdgcn_mfma_f32_32x32x16_bf16(ATT_VF(5), ATT_PF(pb1), S.o0, 0, 0, 0);
;     S.o1 = __builtin_amdgcn_mfma_f32_32x32x16_bf16(ATT_VF(7), ATT_PF(pb1), S.o1, 0, 0, 0);
;     ...
;     float l0 = 0.f, l1 = 0.f, l2 = 0.f, l3 = 0.f;
; #pragma unroll
;     for (int r = 0; r < 16; r += 2) { l0 += sa[r]; l1 += sa[r + 1]; l2 += sb[r]; l3 += sb[r + 1]; }
;     S.l += (l0 + l1) + (l2 + l3);
.Lk1_epi:
	v_exp_f32_e32 v48, v48
	v_exp_f32_e32 v49, v49
	v_exp_f32_e32 v50, v50
	v_exp_f32_e32 v51, v51
	v_exp_f32_e32 v52, v52
	v_exp_f32_e32 v53, v53
	v_exp_f32_e32 v54, v54
	v_exp_f32_e32 v55, v55
	v_cvt_pk_bf16_f32 v152, v48, v49
	v_cvt_pk_bf16_f32 v153, v50, v51
	v_cvt_pk_bf16_f32 v154, v52, v53
	v_cvt_pk_bf16_f32 v155, v54, v55
	v_exp_f32_e32 v56, v56
	v_exp_f32_e32 v57, v57
	v_mfma_f32_32x32x16_bf16 v[32:47], v[112:115], v[152:155], v[32:47]
	v_exp_f32_e32 v58, v58
	v_exp_f32_e32 v59, v59
	v_exp_f32_e32 v60, v60
	v_exp_f32_e32 v61, v61
	v_exp_f32_e32 v62, v62
	v_exp_f32_e32 v63, v63
	v_mfma_f32_32x32x16_bf16 v[16:31], v[108:111], v[152:155], v[16:31]
	v_cvt_pk_bf16_f32 v156, v56, v57
	v_cvt_pk_bf16_f32 v157, v58, v59
	v_cvt_pk_bf16_f32 v158, v60, v61
	v_cvt_pk_bf16_f32 v159, v62, v63
	v_add_f32_e32 v0, v48, v50
	v_add_f32_e32 v0, v0, v52
	v_add_f32_e32 v14, v49, v51
	v_add_f32_e32 v14, v14, v53
	v_mfma_f32_32x32x16_bf16 v[32:47], v[104:107], v[156:159], v[32:47]
	v_exp_f32_e32 v64, v64
	v_exp_f32_e32 v65, v65
	v_exp_f32_e32 v66, v66
	v_exp_f32_e32 v67, v67
	v_exp_f32_e32 v68, v68
	v_exp_f32_e32 v69, v69
	v_exp_f32_e32 v70, v70
	v_exp_f32_e32 v71, v71
	v_mfma_f32_32x32x16_bf16 v[16:31], v[100:103], v[156:159], v[16:31]
	v_cvt_pk_bf16_f32 v160, v64, v65
	v_cvt_pk_bf16_f32 v161, v66, v67
	v_cvt_pk_bf16_f32 v162, v68, v69
	v_cvt_pk_bf16_f32 v163, v70, v71
	v_add_f32_e32 v0, v0, v54
	v_add_f32_e32 v0, v0, v56
	v_add_f32_e32 v14, v14, v55
	v_add_f32_e32 v14, v14, v57
	v_mfma_f32_32x32x16_bf16 v[32:47], v[96:99], v[160:163], v[32:47]
	v_exp_f32_e32 v72, v72
	v_exp_f32_e32 v73, v73
	v_exp_f32_e32 v74, v74
	v_exp_f32_e32 v75, v75
	v_exp_f32_e32 v76, v76
	v_exp_f32_e32 v77, v77
	v_exp_f32_e32 v78, v78
	v_exp_f32_e32 v79, v79
	v_mfma_f32_32x32x16_bf16 v[16:31], v[10:13], v[160:163], v[16:31]
	v_cvt_pk_bf16_f32 v234, v72, v73
	v_cvt_pk_bf16_f32 v235, v74, v75
	v_cvt_pk_bf16_f32 v236, v76, v77
	v_cvt_pk_bf16_f32 v237, v78, v79
	v_add_f32_e32 v0, v0, v58
	v_add_f32_e32 v0, v0, v60
	v_add_f32_e32 v0, v0, v62
	v_add_f32_e32 v14, v14, v59
	v_add_f32_e32 v14, v14, v61
	v_add_f32_e32 v14, v14, v63
	v_mfma_f32_32x32x16_bf16 v[32:47], v[6:9], v[234:237], v[32:47]
	v_add_f32_e32 v15, v64, v66
	v_add_f32_e32 v15, v15, v68
	v_add_f32_e32 v15, v15, v70
	v_add_f32_e32 v15, v15, v72
	v_add_f32_e32 v151, v65, v67
	v_add_f32_e32 v151, v151, v69
	v_add_f32_e32 v151, v151, v71
	v_add_f32_e32 v151, v151, v73
	v_mfma_f32_32x32x16_bf16 v[16:31], v[2:5], v[234:237], v[16:31]
	v_add_f32_e32 v15, v15, v74
	v_add_f32_e32 v15, v15, v76
	v_add_f32_e32 v15, v15, v78
	v_add_f32_e32 v151, v151, v75
	v_add_f32_e32 v151, v151, v77
	v_add_f32_e32 v151, v151, v79
	v_add_f32_e32 v0, v0, v14
	v_add_f32_e32 v15, v15, v151
	v_add_f32_e32 v0, v0, v15
	v_add_f32_e32 v149, v149, v0
	s_nop 7
	s_nop 4
	s_mov_b64 s[0:1], -1
	s_branch .LBB0_596
